# phase 0 filter-MLP unit: biases, frequency scales and layer weights issued at the top of the unit (prologue de-serialisation), the three accumulation loops hand-written with the same fma order
# speedup vs baseline: 1.0045x; 1.0045x over previous
.LBB0_9:
	s_cmpk_gt_i32 s90, 0x33f
	s_cbranch_scc0 .LBB0_39
	s_cmpk_gt_u32 s90, 0x3ff
	s_cbranch_scc0 .LBB0_40
	s_cmpk_lg_i32 s90, 0x510
	s_cbranch_scc0 .LBB0_41
	s_mov_b64 s[92:93], 0x1000
	global_load_dword v223, v[58:59], off
	global_load_dword v224, v[60:61], off
	global_load_dword v190, v[74:75], off
	global_load_dword v191, v[74:75], off offset:256
	global_load_dword v192, v[74:75], off offset:512
	global_load_dword v193, v[74:75], off offset:768
	global_load_dword v194, v[74:75], off offset:1024
	global_load_dword v195, v[74:75], off offset:1280
	global_load_dword v196, v[74:75], off offset:1536
	global_load_dword v197, v[74:75], off offset:1792
	global_load_dword v198, v[74:75], off offset:2048
	global_load_dword v199, v[74:75], off offset:2304
	global_load_dword v200, v[74:75], off offset:2560
	global_load_dword v201, v[74:75], off offset:2816
	global_load_dword v202, v[74:75], off offset:3072
	global_load_dword v203, v[74:75], off offset:3328
	global_load_dword v204, v[74:75], off offset:3584
	global_load_dword v205, v[74:75], off offset:3840
	v_lshl_add_u64 v[50:51], v[74:75], 0, s[92:93]
	global_load_dword v206, v[50:51], off
	global_load_dword v207, v[50:51], off offset:256
	global_load_dword v208, v[50:51], off offset:512
	global_load_dword v209, v[50:51], off offset:768
	global_load_dword v210, v[50:51], off offset:1024
	global_load_dword v211, v[50:51], off offset:1280
	global_load_dword v212, v[50:51], off offset:1536
	global_load_dword v213, v[50:51], off offset:1792
	global_load_dword v214, v[50:51], off offset:2048
	global_load_dword v215, v[50:51], off offset:2304
	global_load_dword v216, v[50:51], off offset:2560
	global_load_dword v217, v[50:51], off offset:2816
	global_load_dword v218, v[50:51], off offset:3072
	global_load_dword v219, v[50:51], off offset:3328
	global_load_dword v220, v[50:51], off offset:3584
	global_load_dword v221, v[50:51], off offset:3840
	v_lshl_add_u64 v[50:51], v[50:51], 0, s[92:93]
	global_load_dword v222, v[50:51], off
	global_load_dword v225, v[62:63], off
	global_load_dword v226, v[60:61], off offset:256
	global_load_dword v126, v[76:77], off
	global_load_dword v127, v[76:77], off offset:256
	global_load_dword v128, v[76:77], off offset:512
	global_load_dword v129, v[76:77], off offset:768
	global_load_dword v130, v[76:77], off offset:1024
	global_load_dword v131, v[76:77], off offset:1280
	global_load_dword v132, v[76:77], off offset:1536
	global_load_dword v133, v[76:77], off offset:1792
	global_load_dword v134, v[76:77], off offset:2048
	global_load_dword v135, v[76:77], off offset:2304
	global_load_dword v136, v[76:77], off offset:2560
	global_load_dword v137, v[76:77], off offset:2816
	global_load_dword v138, v[76:77], off offset:3072
	global_load_dword v139, v[76:77], off offset:3328
	global_load_dword v140, v[76:77], off offset:3584
	global_load_dword v141, v[76:77], off offset:3840
	v_lshl_add_u64 v[50:51], v[76:77], 0, s[92:93]
	global_load_dword v142, v[50:51], off
	global_load_dword v143, v[50:51], off offset:256
	global_load_dword v144, v[50:51], off offset:512
	global_load_dword v145, v[50:51], off offset:768
	global_load_dword v146, v[50:51], off offset:1024
	global_load_dword v147, v[50:51], off offset:1280
	global_load_dword v148, v[50:51], off offset:1536
	global_load_dword v149, v[50:51], off offset:1792
	global_load_dword v150, v[50:51], off offset:2048
	global_load_dword v151, v[50:51], off offset:2304
	global_load_dword v152, v[50:51], off offset:2560
	global_load_dword v153, v[50:51], off offset:2816
	global_load_dword v154, v[50:51], off offset:3072
	global_load_dword v155, v[50:51], off offset:3328
	global_load_dword v156, v[50:51], off offset:3584
	global_load_dword v157, v[50:51], off offset:3840
	v_lshl_add_u64 v[50:51], v[50:51], 0, s[92:93]
	global_load_dword v158, v[50:51], off
	global_load_dword v159, v[50:51], off offset:256
	global_load_dword v160, v[50:51], off offset:512
	global_load_dword v161, v[50:51], off offset:768
	global_load_dword v162, v[50:51], off offset:1024
	global_load_dword v163, v[50:51], off offset:1280
	global_load_dword v164, v[50:51], off offset:1536
	global_load_dword v165, v[50:51], off offset:1792
	global_load_dword v166, v[50:51], off offset:2048
	global_load_dword v167, v[50:51], off offset:2304
	global_load_dword v168, v[50:51], off offset:2560
	global_load_dword v169, v[50:51], off offset:2816
	global_load_dword v170, v[50:51], off offset:3072
	global_load_dword v171, v[50:51], off offset:3328
	global_load_dword v172, v[50:51], off offset:3584
	global_load_dword v173, v[50:51], off offset:3840
	v_lshl_add_u64 v[50:51], v[50:51], 0, s[92:93]
	global_load_dword v174, v[50:51], off
	global_load_dword v175, v[50:51], off offset:256
	global_load_dword v176, v[50:51], off offset:512
	global_load_dword v177, v[50:51], off offset:768
	global_load_dword v178, v[50:51], off offset:1024
	global_load_dword v179, v[50:51], off offset:1280
	global_load_dword v180, v[50:51], off offset:1536
	global_load_dword v181, v[50:51], off offset:1792
	global_load_dword v182, v[50:51], off offset:2048
	global_load_dword v183, v[50:51], off offset:2304
	global_load_dword v184, v[50:51], off offset:2560
	global_load_dword v185, v[50:51], off offset:2816
	global_load_dword v186, v[50:51], off offset:3072
	global_load_dword v187, v[50:51], off offset:3328
	global_load_dword v188, v[50:51], off offset:3584
	global_load_dword v189, v[50:51], off offset:3840
	global_load_dword v227, v[64:65], off
	global_load_dword v228, v[60:61], off offset:512
	v_lshl_add_u32 v2, s90, 4, v100
	s_movk_i32 s14, 0x100
	v_add_u32_e32 v3, 0xffffff00, v2
	v_cmp_gt_i32_e64 s[14:15], s14, v2
	s_nop 1
	v_cndmask_b32_e64 v92, v3, v2, s[14:15]
	s_and_saveexec_b64 s[16:17], s[8:9]
	s_cbranch_execz .LBB0_22
	v_cvt_f32_i32_e32 v3, v92
	v_cndmask_b32_e64 v5, v119, v120, s[14:15]
	s_and_saveexec_b64 s[36:37], s[10:11]
	s_xor_b64 s[36:37], exec, s[36:37]
	s_cbranch_execz .LBB0_19
	v_cvt_f64_u32_e32 v[4:5], v5
	v_div_scale_f64 v[6:7], s[38:39], v[4:5], v[4:5], s[18:19]
	v_rcp_f64_e32 v[8:9], v[6:7]
	v_div_scale_f64 v[10:11], vcc, s[18:19], v[4:5], s[18:19]
	v_fma_f64 v[12:13], -v[6:7], v[8:9], 1.0
	v_fmac_f64_e32 v[8:9], v[8:9], v[12:13]
	v_fma_f64 v[12:13], -v[6:7], v[8:9], 1.0
	v_fmac_f64_e32 v[8:9], v[8:9], v[12:13]
	v_mul_f64 v[12:13], v[10:11], v[8:9]
	v_fma_f64 v[6:7], -v[6:7], v[12:13], v[10:11]
	v_div_fmas_f64 v[6:7], v[6:7], v[8:9], v[12:13]
	v_div_fixup_f64 v[4:5], v[6:7], v[4:5], s[18:19]
	v_cvt_f32_f64_e32 v4, v[4:5]
	v_mul_f32_e32 v3, v3, v4
	v_mul_f32_e32 v3, v102, v3
	v_mul_f32_e32 v4, 0.15915494, v3
	v_rndne_f32_e32 v4, v4
	v_fmac_f32_e32 v3, 0xc0c90fdb, v4
	v_fmac_f32_e32 v3, 0x343bbd2e, v4
	s_and_saveexec_b64 s[38:39], s[12:13]
	s_xor_b64 s[38:39], exec, s[38:39]
	v_mul_f32_e32 v3, 0xbe22f983, v3
	v_sin_f32_e32 v4, v3
	s_andn2_saveexec_b64 s[38:39], s[38:39]
	v_mul_f32_e32 v3, 0.15915494, v3
	v_cos_f32_e32 v4, v3
	s_or_b64 exec, exec, s[38:39]

.LBB0_32:
	s_or_b64 exec, exec, s[36:37]
	s_waitcnt lgkmcnt(0)
	s_barrier
	s_waitcnt vmcnt(63)
	v_mov_b32_e32 v3, v223
	v_mov_b32_e32 v2, v223
	ds_read_b128 v[34:37], v104 offset:0
	ds_read_b128 v[38:41], v104 offset:16
	ds_read_b128 v[42:45], v104 offset:1280
	ds_read_b128 v[46:49], v104 offset:1296
	s_waitcnt lgkmcnt(0)
	v_fmac_f32_e32 v3, v190, v34
	v_fmac_f32_e32 v2, v190, v42
	v_fmac_f32_e32 v3, v191, v35
	v_fmac_f32_e32 v2, v191, v43
	v_fmac_f32_e32 v3, v192, v36
	v_fmac_f32_e32 v2, v192, v44
	v_fmac_f32_e32 v3, v193, v37
	v_fmac_f32_e32 v2, v193, v45
	v_fmac_f32_e32 v3, v194, v38
	v_fmac_f32_e32 v2, v194, v46
	v_fmac_f32_e32 v3, v195, v39
	v_fmac_f32_e32 v2, v195, v47
	v_fmac_f32_e32 v3, v196, v40
	v_fmac_f32_e32 v2, v196, v48
	v_fmac_f32_e32 v3, v197, v41
	v_fmac_f32_e32 v2, v197, v49
	ds_read_b128 v[34:37], v104 offset:32
	ds_read_b128 v[38:41], v104 offset:48
	ds_read_b128 v[42:45], v104 offset:1312
	ds_read_b128 v[46:49], v104 offset:1328
	s_waitcnt lgkmcnt(0)
	v_fmac_f32_e32 v3, v198, v34
	v_fmac_f32_e32 v2, v198, v42
	v_fmac_f32_e32 v3, v199, v35
	v_fmac_f32_e32 v2, v199, v43
	v_fmac_f32_e32 v3, v200, v36
	v_fmac_f32_e32 v2, v200, v44
	v_fmac_f32_e32 v3, v201, v37
	v_fmac_f32_e32 v2, v201, v45
	v_fmac_f32_e32 v3, v202, v38
	v_fmac_f32_e32 v2, v202, v46
	v_fmac_f32_e32 v3, v203, v39
	v_fmac_f32_e32 v2, v203, v47
	v_fmac_f32_e32 v3, v204, v40
	v_fmac_f32_e32 v2, v204, v48
	v_fmac_f32_e32 v3, v205, v41
	v_fmac_f32_e32 v2, v205, v49
	ds_read_b128 v[34:37], v104 offset:64
	ds_read_b128 v[38:41], v104 offset:80
	ds_read_b128 v[42:45], v104 offset:1344
	ds_read_b128 v[46:49], v104 offset:1360
	s_waitcnt lgkmcnt(0)
	v_fmac_f32_e32 v3, v206, v34
	v_fmac_f32_e32 v2, v206, v42
	v_fmac_f32_e32 v3, v207, v35
	v_fmac_f32_e32 v2, v207, v43
	v_fmac_f32_e32 v3, v208, v36
	v_fmac_f32_e32 v2, v208, v44
	v_fmac_f32_e32 v3, v209, v37
	v_fmac_f32_e32 v2, v209, v45
	v_fmac_f32_e32 v3, v210, v38
	v_fmac_f32_e32 v2, v210, v46
	v_fmac_f32_e32 v3, v211, v39
	v_fmac_f32_e32 v2, v211, v47
	v_fmac_f32_e32 v3, v212, v40
	v_fmac_f32_e32 v2, v212, v48
	v_fmac_f32_e32 v3, v213, v41
	v_fmac_f32_e32 v2, v213, v49
	ds_read_b128 v[34:37], v104 offset:96
	ds_read_b128 v[38:41], v104 offset:112
	ds_read_b128 v[42:45], v104 offset:1376
	ds_read_b128 v[46:49], v104 offset:1392
	s_waitcnt lgkmcnt(0)
	v_fmac_f32_e32 v3, v214, v34
	v_fmac_f32_e32 v2, v214, v42
	v_fmac_f32_e32 v3, v215, v35
	v_fmac_f32_e32 v2, v215, v43
	v_fmac_f32_e32 v3, v216, v36
	v_fmac_f32_e32 v2, v216, v44
	v_fmac_f32_e32 v3, v217, v37
	v_fmac_f32_e32 v2, v217, v45
	v_fmac_f32_e32 v3, v218, v38
	v_fmac_f32_e32 v2, v218, v46
	v_fmac_f32_e32 v3, v219, v39
	v_fmac_f32_e32 v2, v219, v47
	v_fmac_f32_e32 v3, v220, v40
	v_fmac_f32_e32 v2, v220, v48
	v_fmac_f32_e32 v3, v221, v41
	v_fmac_f32_e32 v2, v221, v49
	ds_read_b128 v[34:37], v104 offset:128
	ds_read_b128 v[38:41], v104 offset:144
	ds_read_b128 v[42:45], v104 offset:1408
	ds_read_b128 v[46:49], v104 offset:1424
	s_waitcnt lgkmcnt(0)
	v_fmac_f32_e32 v3, v222, v34
	v_fmac_f32_e32 v2, v222, v42
	global_load_dword v190, v[78:79], off
	global_load_dword v191, v[78:79], off offset:256
	global_load_dword v192, v[78:79], off offset:512
	global_load_dword v193, v[78:79], off offset:768
	global_load_dword v194, v[78:79], off offset:1024
	global_load_dword v195, v[78:79], off offset:1280
	global_load_dword v196, v[78:79], off offset:1536
	global_load_dword v197, v[78:79], off offset:1792
	global_load_dword v198, v[78:79], off offset:2048
	global_load_dword v199, v[78:79], off offset:2304
	global_load_dword v200, v[78:79], off offset:2560
	global_load_dword v201, v[78:79], off offset:2816
	global_load_dword v202, v[78:79], off offset:3072
	global_load_dword v203, v[78:79], off offset:3328
	global_load_dword v204, v[78:79], off offset:3584
	global_load_dword v205, v[78:79], off offset:3840
	v_lshl_add_u64 v[50:51], v[78:79], 0, s[92:93]
	global_load_dword v206, v[50:51], off
	global_load_dword v207, v[50:51], off offset:256
	global_load_dword v208, v[50:51], off offset:512
	global_load_dword v209, v[50:51], off offset:768
	global_load_dword v210, v[50:51], off offset:1024
	global_load_dword v211, v[50:51], off offset:1280
	global_load_dword v212, v[50:51], off offset:1536
	global_load_dword v213, v[50:51], off offset:1792
	global_load_dword v214, v[50:51], off offset:2048
	global_load_dword v215, v[50:51], off offset:2304
	global_load_dword v216, v[50:51], off offset:2560
	global_load_dword v217, v[50:51], off offset:2816
	global_load_dword v218, v[50:51], off offset:3072
	global_load_dword v219, v[50:51], off offset:3328
	global_load_dword v220, v[50:51], off offset:3584
	global_load_dword v221, v[50:51], off offset:3840
	v_lshl_add_u64 v[50:51], v[50:51], 0, s[92:93]
	global_load_dword v222, v[50:51], off
	global_load_dword v229, v[50:51], off offset:256
	global_load_dword v230, v[50:51], off offset:512
	global_load_dword v231, v[50:51], off offset:768
	global_load_dword v232, v[50:51], off offset:1024
	global_load_dword v233, v[50:51], off offset:1280
	global_load_dword v234, v[50:51], off offset:1536
	global_load_dword v235, v[50:51], off offset:1792
	global_load_dword v236, v[50:51], off offset:2048
	global_load_dword v237, v[50:51], off offset:2304
	global_load_dword v238, v[50:51], off offset:2560
	global_load_dword v239, v[50:51], off offset:2816
	global_load_dword v14, v[50:51], off offset:3072
	global_load_dword v15, v[50:51], off offset:3328
	global_load_dword v16, v[50:51], off offset:3584
	global_load_dword v17, v[50:51], off offset:3840
	v_lshl_add_u64 v[50:51], v[50:51], 0, s[92:93]
	global_load_dword v18, v[50:51], off
	global_load_dword v19, v[50:51], off offset:256
	global_load_dword v20, v[50:51], off offset:512
	global_load_dword v21, v[50:51], off offset:768
	global_load_dword v22, v[50:51], off offset:1024
	global_load_dword v23, v[50:51], off offset:1280
	global_load_dword v24, v[50:51], off offset:1536
	global_load_dword v25, v[50:51], off offset:1792
	global_load_dword v26, v[50:51], off offset:2048
	global_load_dword v27, v[50:51], off offset:2304
	global_load_dword v28, v[50:51], off offset:2560
	global_load_dword v29, v[50:51], off offset:2816
	global_load_dword v30, v[50:51], off offset:3072
	global_load_dword v31, v[50:51], off offset:3328
	global_load_dword v32, v[50:51], off offset:3584
	global_load_dword v33, v[50:51], off offset:3840
	v_mov_b32_e32 v4, v224
	s_mov_b64 s[36:37], 0
	v_mov_b32_e32 v54, v115
	v_mul_f32_e32 v3, v3, v4
	v_mul_f32_e32 v2, v2, v4
	v_mul_f32_e32 v4, 0.15915494, v3
	v_mul_f32_e32 v5, 0.15915494, v2
	v_rndne_f32_e32 v4, v4
	v_rndne_f32_e32 v5, v5
	v_fmac_f32_e32 v3, 0xc0c90fdb, v4
	v_fmac_f32_e32 v2, 0xc0c90fdb, v5
	v_fmac_f32_e32 v3, 0x343bbd2e, v4
	v_fmac_f32_e32 v2, 0x343bbd2e, v5
	v_mul_f32_e32 v3, 0.15915494, v3
	v_mul_f32_e32 v2, 0.15915494, v2
	v_sin_f32_e32 v3, v3
	v_sin_f32_e32 v2, v2
	ds_write_b32 v105, v3 offset:4096
	ds_write_b32 v106, v2 offset:6144
	s_waitcnt lgkmcnt(0)
	s_barrier
	s_waitcnt vmcnt(63)
	v_mov_b32_e32 v97, v225
	v_mov_b32_e32 v96, v225
	ds_read_b128 v[34:37], v54 offset:0
	ds_read_b128 v[38:41], v54 offset:16
	ds_read_b128 v[42:45], v54 offset:2048
	ds_read_b128 v[46:49], v54 offset:2064
	s_waitcnt lgkmcnt(0)
	v_fmac_f32_e32 v97, v126, v34
	v_fmac_f32_e32 v96, v126, v42
	v_fmac_f32_e32 v97, v127, v35
	v_fmac_f32_e32 v96, v127, v43
	v_fmac_f32_e32 v97, v128, v36
	v_fmac_f32_e32 v96, v128, v44
	v_fmac_f32_e32 v97, v129, v37
	v_fmac_f32_e32 v96, v129, v45
	v_fmac_f32_e32 v97, v130, v38
	v_fmac_f32_e32 v96, v130, v46
	v_fmac_f32_e32 v97, v131, v39
	v_fmac_f32_e32 v96, v131, v47
	v_fmac_f32_e32 v97, v132, v40
	v_fmac_f32_e32 v96, v132, v48
	v_fmac_f32_e32 v97, v133, v41
	v_fmac_f32_e32 v96, v133, v49
	ds_read_b128 v[34:37], v54 offset:32
	ds_read_b128 v[38:41], v54 offset:48
	ds_read_b128 v[42:45], v54 offset:2080
	ds_read_b128 v[46:49], v54 offset:2096
	s_waitcnt lgkmcnt(0)
	v_fmac_f32_e32 v97, v134, v34
	v_fmac_f32_e32 v96, v134, v42
	v_fmac_f32_e32 v97, v135, v35
	v_fmac_f32_e32 v96, v135, v43
	v_fmac_f32_e32 v97, v136, v36
	v_fmac_f32_e32 v96, v136, v44
	v_fmac_f32_e32 v97, v137, v37
	v_fmac_f32_e32 v96, v137, v45
	v_fmac_f32_e32 v97, v138, v38
	v_fmac_f32_e32 v96, v138, v46
	v_fmac_f32_e32 v97, v139, v39
	v_fmac_f32_e32 v96, v139, v47
	v_fmac_f32_e32 v97, v140, v40
	v_fmac_f32_e32 v96, v140, v48
	v_fmac_f32_e32 v97, v141, v41
	v_fmac_f32_e32 v96, v141, v49
	ds_read_b128 v[34:37], v54 offset:64
	ds_read_b128 v[38:41], v54 offset:80
	ds_read_b128 v[42:45], v54 offset:2112
	ds_read_b128 v[46:49], v54 offset:2128
	s_waitcnt lgkmcnt(0)
	v_fmac_f32_e32 v97, v142, v34
	v_fmac_f32_e32 v96, v142, v42
	v_fmac_f32_e32 v97, v143, v35
	v_fmac_f32_e32 v96, v143, v43
	v_fmac_f32_e32 v97, v144, v36
	v_fmac_f32_e32 v96, v144, v44
	v_fmac_f32_e32 v97, v145, v37
	v_fmac_f32_e32 v96, v145, v45
	v_fmac_f32_e32 v97, v146, v38
	v_fmac_f32_e32 v96, v146, v46
	v_fmac_f32_e32 v97, v147, v39
	v_fmac_f32_e32 v96, v147, v47
	v_fmac_f32_e32 v97, v148, v40
	v_fmac_f32_e32 v96, v148, v48
	v_fmac_f32_e32 v97, v149, v41
	v_fmac_f32_e32 v96, v149, v49
	ds_read_b128 v[34:37], v54 offset:96
	ds_read_b128 v[38:41], v54 offset:112
	ds_read_b128 v[42:45], v54 offset:2144
	ds_read_b128 v[46:49], v54 offset:2160
	s_waitcnt lgkmcnt(0)
	v_fmac_f32_e32 v97, v150, v34
	v_fmac_f32_e32 v96, v150, v42
	v_fmac_f32_e32 v97, v151, v35
	v_fmac_f32_e32 v96, v151, v43
	v_fmac_f32_e32 v97, v152, v36
	v_fmac_f32_e32 v96, v152, v44
	v_fmac_f32_e32 v97, v153, v37
	v_fmac_f32_e32 v96, v153, v45
	v_fmac_f32_e32 v97, v154, v38
	v_fmac_f32_e32 v96, v154, v46
	v_fmac_f32_e32 v97, v155, v39
	v_fmac_f32_e32 v96, v155, v47
	v_fmac_f32_e32 v97, v156, v40
	v_fmac_f32_e32 v96, v156, v48
	v_fmac_f32_e32 v97, v157, v41
	v_fmac_f32_e32 v96, v157, v49
	ds_read_b128 v[34:37], v54 offset:128
	ds_read_b128 v[38:41], v54 offset:144
	ds_read_b128 v[42:45], v54 offset:2176
	ds_read_b128 v[46:49], v54 offset:2192
	s_waitcnt lgkmcnt(0)
	v_fmac_f32_e32 v97, v158, v34
	v_fmac_f32_e32 v96, v158, v42
	v_fmac_f32_e32 v97, v159, v35
	v_fmac_f32_e32 v96, v159, v43
	v_fmac_f32_e32 v97, v160, v36
	v_fmac_f32_e32 v96, v160, v44
	v_fmac_f32_e32 v97, v161, v37
	v_fmac_f32_e32 v96, v161, v45
	v_fmac_f32_e32 v97, v162, v38
	v_fmac_f32_e32 v96, v162, v46
	v_fmac_f32_e32 v97, v163, v39
	v_fmac_f32_e32 v96, v163, v47
	v_fmac_f32_e32 v97, v164, v40
	v_fmac_f32_e32 v96, v164, v48
	v_fmac_f32_e32 v97, v165, v41
	v_fmac_f32_e32 v96, v165, v49
	ds_read_b128 v[34:37], v54 offset:160
	ds_read_b128 v[38:41], v54 offset:176
	ds_read_b128 v[42:45], v54 offset:2208
	ds_read_b128 v[46:49], v54 offset:2224
	s_waitcnt lgkmcnt(0)
	v_fmac_f32_e32 v97, v166, v34
	v_fmac_f32_e32 v96, v166, v42
	v_fmac_f32_e32 v97, v167, v35
	v_fmac_f32_e32 v96, v167, v43
	v_fmac_f32_e32 v97, v168, v36
	v_fmac_f32_e32 v96, v168, v44
	v_fmac_f32_e32 v97, v169, v37
	v_fmac_f32_e32 v96, v169, v45
	v_fmac_f32_e32 v97, v170, v38
	v_fmac_f32_e32 v96, v170, v46
	v_fmac_f32_e32 v97, v171, v39
	v_fmac_f32_e32 v96, v171, v47
	v_fmac_f32_e32 v97, v172, v40
	v_fmac_f32_e32 v96, v172, v48
	v_fmac_f32_e32 v97, v173, v41
	v_fmac_f32_e32 v96, v173, v49
	ds_read_b128 v[34:37], v54 offset:192
	ds_read_b128 v[38:41], v54 offset:208
	ds_read_b128 v[42:45], v54 offset:2240
	ds_read_b128 v[46:49], v54 offset:2256
	s_waitcnt lgkmcnt(0)
	v_fmac_f32_e32 v97, v174, v34
	v_fmac_f32_e32 v96, v174, v42
	v_fmac_f32_e32 v97, v175, v35
	v_fmac_f32_e32 v96, v175, v43
	v_fmac_f32_e32 v97, v176, v36
	v_fmac_f32_e32 v96, v176, v44
	v_fmac_f32_e32 v97, v177, v37
	v_fmac_f32_e32 v96, v177, v45
	v_fmac_f32_e32 v97, v178, v38
	v_fmac_f32_e32 v96, v178, v46
	v_fmac_f32_e32 v97, v179, v39
	v_fmac_f32_e32 v96, v179, v47
	v_fmac_f32_e32 v97, v180, v40
	v_fmac_f32_e32 v96, v180, v48
	v_fmac_f32_e32 v97, v181, v41
	v_fmac_f32_e32 v96, v181, v49
	ds_read_b128 v[34:37], v54 offset:224
	ds_read_b128 v[38:41], v54 offset:240
	ds_read_b128 v[42:45], v54 offset:2272
	ds_read_b128 v[46:49], v54 offset:2288
	s_waitcnt lgkmcnt(0)
	v_fmac_f32_e32 v97, v182, v34
	v_fmac_f32_e32 v96, v182, v42
	v_fmac_f32_e32 v97, v183, v35
	v_fmac_f32_e32 v96, v183, v43
	v_fmac_f32_e32 v97, v184, v36
	v_fmac_f32_e32 v96, v184, v44
	v_fmac_f32_e32 v97, v185, v37
	v_fmac_f32_e32 v96, v185, v45
	v_fmac_f32_e32 v97, v186, v38
	v_fmac_f32_e32 v96, v186, v46
	v_fmac_f32_e32 v97, v187, v39
	v_fmac_f32_e32 v96, v187, v47
	v_fmac_f32_e32 v97, v188, v40
	v_fmac_f32_e32 v96, v188, v48
	v_fmac_f32_e32 v97, v189, v41
	v_fmac_f32_e32 v96, v189, v49
	v_mov_b32_e32 v2, v226
	s_mov_b64 s[36:37], 0
	v_mov_b32_e32 v54, v116
	v_mul_f32_e32 v3, v97, v2
	v_mul_f32_e32 v2, v96, v2
	v_mul_f32_e32 v4, 0.15915494, v3
	v_mul_f32_e32 v5, 0.15915494, v2
	v_rndne_f32_e32 v4, v4
	v_rndne_f32_e32 v5, v5
	v_fmac_f32_e32 v3, 0xc0c90fdb, v4
	v_fmac_f32_e32 v2, 0xc0c90fdb, v5
	v_fmac_f32_e32 v3, 0x343bbd2e, v4
	v_fmac_f32_e32 v2, 0x343bbd2e, v5
	v_mul_f32_e32 v3, 0.15915494, v3
	v_mul_f32_e32 v2, 0.15915494, v2
	v_sin_f32_e32 v3, v3
	v_sin_f32_e32 v2, v2
	ds_write_b32 v105, v3 offset:8192
	ds_write_b32 v106, v2 offset:10240
	s_waitcnt lgkmcnt(0)
	s_barrier
	s_waitcnt vmcnt(0)
	v_mov_b32_e32 v97, v227
	v_mov_b32_e32 v96, v227
	ds_read_b128 v[34:37], v54 offset:0
	ds_read_b128 v[38:41], v54 offset:16
	ds_read_b128 v[42:45], v54 offset:2048
	ds_read_b128 v[46:49], v54 offset:2064
	s_waitcnt lgkmcnt(0)
	v_fmac_f32_e32 v97, v190, v34
	v_fmac_f32_e32 v96, v190, v42
	v_fmac_f32_e32 v97, v191, v35
	v_fmac_f32_e32 v96, v191, v43
	v_fmac_f32_e32 v97, v192, v36
	v_fmac_f32_e32 v96, v192, v44
	v_fmac_f32_e32 v97, v193, v37
	v_fmac_f32_e32 v96, v193, v45
	v_fmac_f32_e32 v97, v194, v38
	v_fmac_f32_e32 v96, v194, v46
	v_fmac_f32_e32 v97, v195, v39
	v_fmac_f32_e32 v96, v195, v47
	v_fmac_f32_e32 v97, v196, v40
	v_fmac_f32_e32 v96, v196, v48
	v_fmac_f32_e32 v97, v197, v41
	v_fmac_f32_e32 v96, v197, v49
	ds_read_b128 v[34:37], v54 offset:32
	ds_read_b128 v[38:41], v54 offset:48
	ds_read_b128 v[42:45], v54 offset:2080
	ds_read_b128 v[46:49], v54 offset:2096
	s_waitcnt lgkmcnt(0)
	v_fmac_f32_e32 v97, v198, v34
	v_fmac_f32_e32 v96, v198, v42
	v_fmac_f32_e32 v97, v199, v35
	v_fmac_f32_e32 v96, v199, v43
	v_fmac_f32_e32 v97, v200, v36
	v_fmac_f32_e32 v96, v200, v44
	v_fmac_f32_e32 v97, v201, v37
	v_fmac_f32_e32 v96, v201, v45
	v_fmac_f32_e32 v97, v202, v38
	v_fmac_f32_e32 v96, v202, v46
	v_fmac_f32_e32 v97, v203, v39
	v_fmac_f32_e32 v96, v203, v47
	v_fmac_f32_e32 v97, v204, v40
	v_fmac_f32_e32 v96, v204, v48
	v_fmac_f32_e32 v97, v205, v41
	v_fmac_f32_e32 v96, v205, v49
	ds_read_b128 v[34:37], v54 offset:64
	ds_read_b128 v[38:41], v54 offset:80
	ds_read_b128 v[42:45], v54 offset:2112
	ds_read_b128 v[46:49], v54 offset:2128
	s_waitcnt lgkmcnt(0)
	v_fmac_f32_e32 v97, v206, v34
	v_fmac_f32_e32 v96, v206, v42
	v_fmac_f32_e32 v97, v207, v35
	v_fmac_f32_e32 v96, v207, v43
	v_fmac_f32_e32 v97, v208, v36
	v_fmac_f32_e32 v96, v208, v44
	v_fmac_f32_e32 v97, v209, v37
	v_fmac_f32_e32 v96, v209, v45
	v_fmac_f32_e32 v97, v210, v38
	v_fmac_f32_e32 v96, v210, v46
	v_fmac_f32_e32 v97, v211, v39
	v_fmac_f32_e32 v96, v211, v47
	v_fmac_f32_e32 v97, v212, v40
	v_fmac_f32_e32 v96, v212, v48
	v_fmac_f32_e32 v97, v213, v41
	v_fmac_f32_e32 v96, v213, v49
	ds_read_b128 v[34:37], v54 offset:96
	ds_read_b128 v[38:41], v54 offset:112
	ds_read_b128 v[42:45], v54 offset:2144
	ds_read_b128 v[46:49], v54 offset:2160
	s_waitcnt lgkmcnt(0)
	v_fmac_f32_e32 v97, v214, v34
	v_fmac_f32_e32 v96, v214, v42
	v_fmac_f32_e32 v97, v215, v35
	v_fmac_f32_e32 v96, v215, v43
	v_fmac_f32_e32 v97, v216, v36
	v_fmac_f32_e32 v96, v216, v44
	v_fmac_f32_e32 v97, v217, v37
	v_fmac_f32_e32 v96, v217, v45
	v_fmac_f32_e32 v97, v218, v38
	v_fmac_f32_e32 v96, v218, v46
	v_fmac_f32_e32 v97, v219, v39
	v_fmac_f32_e32 v96, v219, v47
	v_fmac_f32_e32 v97, v220, v40
	v_fmac_f32_e32 v96, v220, v48
	v_fmac_f32_e32 v97, v221, v41
	v_fmac_f32_e32 v96, v221, v49
	ds_read_b128 v[34:37], v54 offset:128
	ds_read_b128 v[38:41], v54 offset:144
	ds_read_b128 v[42:45], v54 offset:2176
	ds_read_b128 v[46:49], v54 offset:2192
	s_waitcnt lgkmcnt(0)
	v_fmac_f32_e32 v97, v222, v34
	v_fmac_f32_e32 v96, v222, v42
	v_fmac_f32_e32 v97, v229, v35
	v_fmac_f32_e32 v96, v229, v43
	v_fmac_f32_e32 v97, v230, v36
	v_fmac_f32_e32 v96, v230, v44
	v_fmac_f32_e32 v97, v231, v37
	v_fmac_f32_e32 v96, v231, v45
	v_fmac_f32_e32 v97, v232, v38
	v_fmac_f32_e32 v96, v232, v46
	v_fmac_f32_e32 v97, v233, v39
	v_fmac_f32_e32 v96, v233, v47
	v_fmac_f32_e32 v97, v234, v40
	v_fmac_f32_e32 v96, v234, v48
	v_fmac_f32_e32 v97, v235, v41
	v_fmac_f32_e32 v96, v235, v49
	ds_read_b128 v[34:37], v54 offset:160
	ds_read_b128 v[38:41], v54 offset:176
	ds_read_b128 v[42:45], v54 offset:2208
	ds_read_b128 v[46:49], v54 offset:2224
	s_waitcnt lgkmcnt(0)
	v_fmac_f32_e32 v97, v236, v34
	v_fmac_f32_e32 v96, v236, v42
	v_fmac_f32_e32 v97, v237, v35
	v_fmac_f32_e32 v96, v237, v43
	v_fmac_f32_e32 v97, v238, v36
	v_fmac_f32_e32 v96, v238, v44
	v_fmac_f32_e32 v97, v239, v37
	v_fmac_f32_e32 v96, v239, v45
	v_fmac_f32_e32 v97, v14, v38
	v_fmac_f32_e32 v96, v14, v46
	v_fmac_f32_e32 v97, v15, v39
	v_fmac_f32_e32 v96, v15, v47
	v_fmac_f32_e32 v97, v16, v40
	v_fmac_f32_e32 v96, v16, v48
	v_fmac_f32_e32 v97, v17, v41
	v_fmac_f32_e32 v96, v17, v49
	ds_read_b128 v[34:37], v54 offset:192
	ds_read_b128 v[38:41], v54 offset:208
	ds_read_b128 v[42:45], v54 offset:2240
	ds_read_b128 v[46:49], v54 offset:2256
	s_waitcnt lgkmcnt(0)
	v_fmac_f32_e32 v97, v18, v34
	v_fmac_f32_e32 v96, v18, v42
	v_fmac_f32_e32 v97, v19, v35
	v_fmac_f32_e32 v96, v19, v43
	v_fmac_f32_e32 v97, v20, v36
	v_fmac_f32_e32 v96, v20, v44
	v_fmac_f32_e32 v97, v21, v37
	v_fmac_f32_e32 v96, v21, v45
	v_fmac_f32_e32 v97, v22, v38
	v_fmac_f32_e32 v96, v22, v46
	v_fmac_f32_e32 v97, v23, v39
	v_fmac_f32_e32 v96, v23, v47
	v_fmac_f32_e32 v97, v24, v40
	v_fmac_f32_e32 v96, v24, v48
	v_fmac_f32_e32 v97, v25, v41
	v_fmac_f32_e32 v96, v25, v49
	ds_read_b128 v[34:37], v54 offset:224
	ds_read_b128 v[38:41], v54 offset:240
	ds_read_b128 v[42:45], v54 offset:2272
	ds_read_b128 v[46:49], v54 offset:2288
	s_waitcnt lgkmcnt(0)
	v_fmac_f32_e32 v97, v26, v34
	v_fmac_f32_e32 v96, v26, v42
	v_fmac_f32_e32 v97, v27, v35
	v_fmac_f32_e32 v96, v27, v43
	v_fmac_f32_e32 v97, v28, v36
	v_fmac_f32_e32 v96, v28, v44
	v_fmac_f32_e32 v97, v29, v37
	v_fmac_f32_e32 v96, v29, v45
	v_fmac_f32_e32 v97, v30, v38
	v_fmac_f32_e32 v96, v30, v46
	v_fmac_f32_e32 v97, v31, v39
	v_fmac_f32_e32 v96, v31, v47
	v_fmac_f32_e32 v97, v32, v40
	v_fmac_f32_e32 v96, v32, v48
	v_fmac_f32_e32 v97, v33, v41
	v_fmac_f32_e32 v96, v33, v49
	v_mov_b32_e32 v10, v228
	v_mov_b32_e32 v6, s3
	v_mov_b32_e32 v7, s74
	v_mov_b32_e32 v8, s33
	v_mov_b32_e32 v9, s57
	v_mov_b32_e32 v95, v55
	v_mov_b32_e32 v93, v55
	v_cndmask_b32_e64 v3, v6, v7, s[16:17]
	v_cndmask_b32_e64 v2, v8, v9, s[16:17]
	v_lshlrev_b64 v[4:5], 7, v[94:95]
	v_cndmask_b32_e64 v7, v6, v7, s[14:15]
	v_cndmask_b32_e64 v6, v8, v9, s[14:15]
	v_lshlrev_b64 v[8:9], 7, v[92:93]
	v_mov_b32_e32 v89, v55
	v_lshl_add_u64 v[2:3], v[2:3], 0, v[4:5]
	v_lshl_add_u64 v[4:5], v[6:7], 0, v[8:9]
	v_cndmask_b32_e64 v54, v122, v123, s[16:17]
	v_lshl_add_u64 v[8:9], v[4:5], 0, v[88:89]
	v_lshl_add_u64 v[6:7], v[2:3], 0, v[54:55]
	v_cndmask_b32_e64 v54, v122, v123, s[14:15]
	v_lshl_add_u64 v[4:5], v[4:5], 0, v[54:55]
	v_lshl_add_u64 v[4:5], v[4:5], 0, v[88:89]
	v_lshl_add_u64 v[2:3], v[2:3], 0, v[88:89]
	v_lshl_add_u64 v[6:7], v[6:7], 0, v[88:89]
	s_mov_b64 s[14:15], -1
	s_waitcnt vmcnt(0)
	v_mul_f32_e32 v11, v97, v10
	v_mul_f32_e32 v10, v96, v10
	v_mul_f32_e32 v12, 0.15915494, v11
	v_mul_f32_e32 v13, 0.15915494, v10
	v_rndne_f32_e32 v12, v12
	v_rndne_f32_e32 v13, v13
	v_fmac_f32_e32 v11, 0xc0c90fdb, v12
	v_fmac_f32_e32 v10, 0xc0c90fdb, v13
	v_fmac_f32_e32 v11, 0x343bbd2e, v12
	v_fmac_f32_e32 v10, 0x343bbd2e, v13
	v_mul_f32_e32 v11, 0.15915494, v11
	v_mul_f32_e32 v10, 0.15915494, v10
	v_sin_f32_e32 v11, v11
	v_sin_f32_e32 v10, v10
	v_cvt_pk_bf16_f32 v12, v11, s0
	v_cvt_pk_bf16_f32 v13, v10, s0
	global_store_short v[8:9], v12, off
	v_lshlrev_b32_e32 v8, 16, v12
	v_lshlrev_b32_e32 v9, 16, v13
	v_sub_f32_e32 v8, v11, v8
	v_sub_f32_e32 v9, v10, v9
	v_cvt_pk_bf16_f32 v8, v8, s0
	v_cvt_pk_bf16_f32 v9, v9, s0
	global_store_short v[4:5], v8, off
	global_store_short v[2:3], v13, off
	global_store_short v[6:7], v9, off
	s_barrier
	s_branch .LBB0_45
